# speedup vs baseline: 1.0057x; 1.0057x over previous
; __device__ __forceinline__ int v_st(int k, int c) { const int kk = (k & ~0xC) | ((k & 4) << 1) | ((k & 8) >> 1); return ((kk >> 3) * 4 + (c >> 5)) * 512 + ((kk & 7) * 32 + (c & 31)) * 2; }
; __device__ __forceinline__ int v_rd_base(int lane) { return ((lane & 3) << 3) | (((lane >> 2) & 3) << 6) | (((lane >> 4) & 1) << 5) | (((lane >> 5) & 1) << 8); }
; template <bool META>
; __device__ __forceinline__ void attn_unit(const bf16_t* Q, bf16_t* Oo, const bf16_t* __restrict__ Kb, const bf16_t* __restrict__ Vb, int b, int kvh, int h, int qb, char* lds, const int tid, const float* qn, const float* RT) {
;     ...
;   const int wid = tid >> 6, lane = tid & 63, r32 = lane & 31, hi = lane >> 5;
;   bf16_t* V_lds = (bf16_t*)lds; bf16_t* K_lds = (bf16_t*)(lds + 3 * SHM_V);
;   float* ws = (float*)(lds + 3 * SHM_V + 3 * SHM_K) + wid * 64; float* li_l = ws; float* al_l = ws + 32;
;   float m_reg = -1e30f, l_reg = 0; f32x16 o[4] = {}; bf16x8 qr[8];
;   const bf16_t* Kh = Kb + kvh * 128; const bf16_t* Vh = Vb + kvh * 128;
;   const long kv0 = (long)b * SEQ, mrow = NREAL + NMETA * b;
;   { const int sq = qb * 256 + wid * 32 + r32;
;     load_q_roped(Q + (size_t)(b * SEQ + sq) * 1024 + h * 128 + hi * 8, qn + hi * 8, RT, sq >> 6, sq & 63, hi, lane, qr); }
;   const int sr = tid >> 4, sc = (tid & 15) * 8, vst0 = v_st(sr, sc), vst1 = v_st(32 + sr, sc);
;   const int vb0 = (int)(uintptr_t)V_lds + v_rd_base(lane);
;   const unsigned lo0 = (unsigned)(sr * LDK + sc) * 2u;
.LBB0_255:
	s_and_b64 vcc, exec, s[0:1]
	s_cbranch_vccz .LBB0_348
	s_cmpk_gt_i32 s50, 0x3ff
	s_cbranch_scc1 .LBB0_274
	v_readlane_b32 s0, v255, 13
	s_lshl_b32 s0, s0, 7
	s_ashr_i32 s1, s0, 31
	s_lshl_b64 s[0:1], s[0:1], 2
	s_add_u32 s0, s68, s0
	s_addc_u32 s1, s69, s1
	v_readlane_b32 s2, v255, 24
	v_readlane_b32 s3, v255, 25
	s_add_u32 s48, s2, 0x3d7f5100
	s_addc_u32 s49, s3, 0
	v_and_b32_e32 v0, 0x3fffffc0, v208
	s_add_i32 s2, 0, 0x18000
	v_lshl_add_u32 v173, v0, 2, s2
	v_ashrrev_i32_e32 v0, 1, v208
	v_and_b32_e32 v2, 63, v208
	v_and_b32_e32 v172, 0xffffffe0, v0
	v_and_b32_e32 v0, 32, v208
	v_lshl_add_u64 v[164:165], s[0:1], 0, v[0:1]
	v_lshlrev_b32_e32 v0, 2, v2
	v_xor_b32_e32 v252, 0x80, v0
	v_ashrrev_i32_e32 v0, 4, v208
	v_and_b32_e32 v5, 0xfffff0, v0
	s_waitcnt vmcnt(0)
	v_lshlrev_b32_e32 v6, 1, v0
	s_waitcnt lgkmcnt(0)
	v_lshlrev_b32_e32 v3, 3, v208
	v_and_or_b32 v5, v6, 8, v5
	v_and_b32_e32 v4, 0x78, v3
	v_lshrrev_b32_e32 v6, 1, v0
	v_lshrrev_b32_e32 v5, 1, v5
	v_bfe_u32 v3, v3, 5, 2
	v_and_b32_e32 v7, 3, v0
	v_or_b32_e32 v5, v5, v3
	v_and_or_b32 v6, v6, 4, v7
	v_lshlrev_b32_e32 v7, 1, v4
	v_lshlrev_b32_e32 v5, 9, v5
	v_lshlrev_b32_e32 v6, 6, v6
	v_and_b32_e32 v8, 48, v7
	v_or3_b32 v176, v5, v6, v8
	v_add_u32_e32 v5, 32, v0
	v_and_b32_e32 v9, 0xfffff0, v5
	v_lshlrev_b32_e32 v10, 1, v5
	v_and_or_b32 v9, v10, 8, v9
	v_lshrrev_b32_e32 v9, 1, v9
	v_or_b32_e32 v3, v9, v3
	v_lshlrev_b32_e32 v3, 9, v3
	v_or3_b32 v177, v3, v6, v8
	v_lshlrev_b32_e32 v6, 4, v208
	v_lshlrev_b32_e32 v3, 3, v2
	v_and_b32_e32 v8, 0xc0, v6
	v_lshlrev_b32_e32 v9, 1, v208
	v_and_or_b32 v8, v3, 24, v8
	v_and_b32_e32 v9, 32, v9
	v_and_b32_e32 v3, 0x100, v3
	s_cmp_lg_u32 0, -1
	v_or3_b32 v3, v8, v9, v3
	s_cselect_b32 s0, 0, 0
	v_lshlrev_b32_e32 v0, 8, v0
	v_add_u32_e32 v178, s0, v3
	v_or_b32_e32 v3, v0, v4
	v_bfe_u32 v11, v208, 5, 1
	v_lshlrev_b32_e32 v166, 1, v3
	v_and_b32_e32 v3, 0xf0, v208
	v_and_b32_e32 v163, 31, v208
	v_bitop3_b32 v179, v7, v0, v3 bitop3:0xde
	v_lshlrev_b32_e32 v0, 8, v5
	v_lshlrev_b32_e32 v181, 4, v11
	v_bitop3_b32 v180, v7, v0, v3 bitop3:0xde
	v_lshlrev_b32_e32 v0, 8, v163
	v_and_b32_e32 v3, 0xf0, v6
	v_or_b32_e32 v4, 32, v181
	v_bitop3_b32 v183, v4, v0, v3 bitop3:0xde
	v_or_b32_e32 v4, 64, v181
	v_bitop3_b32 v184, v4, v0, v3 bitop3:0xde
	v_or_b32_e32 v4, 0x60, v181
	v_bitop3_b32 v185, v4, v0, v3 bitop3:0xde
	v_or_b32_e32 v4, 0x80, v181
	v_bitop3_b32 v186, v4, v0, v3 bitop3:0xde
	v_or_b32_e32 v4, 0xa0, v181
	v_bitop3_b32 v187, v4, v0, v3 bitop3:0xde
	v_or_b32_e32 v4, 0xc0, v181
	v_bitop3_b32 v188, v4, v0, v3 bitop3:0xde
	v_or_b32_e32 v4, 0xe0, v181
	v_lshlrev_b32_e32 v162, 3, v11
	v_mov_b32_e32 v167, v1
	v_bitop3_b32 v182, v181, v0, v3 bitop3:0xde
	v_bitop3_b32 v189, v4, v0, v3 bitop3:0xde
	v_cmp_gt_u32_e64 s[38:39], 32, v2
	v_lshl_add_u32 v190, v163, 2, v173
	s_mov_b32 s2, s50
	s_branch .LBB0_259

; #define SBAR() __builtin_amdgcn_sched_barrier(0)
; #define SLOAD(i, t) do { const long rb_ = TROW(t); const char* vt_ = (const char*)Vh + rb_ * (LDK * 2); const char* kt_ = (const char*)Kh + rb_ * (LDK * 2); \
;     sr_[i].vs0 = *(const bf16x8*)(vt_ + lo0); sr_[i].vs1 = *(const bf16x8*)(vt_ + lo0 + 32 * LDK * 2); \
;     sr_[i].ks0 = *(const bf16x8*)(kt_ + lo0); sr_[i].ks1 = *(const bf16x8*)(kt_ + lo0 + 32 * LDK * 2); } while (0)
; __device__ __forceinline__ void finishSM(f32x16& p0, f32x16& p1, float alpha, float& l_reg, bf16x8& pa0, bf16x8& pa1, bf16x8& pa2, bf16x8& pa3) {
; #pragma unroll
;   for (int r = 0; r < 16; ++r) p1[r] = __builtin_amdgcn_exp2f(p1[r]);
;   float ps = 0;
; #pragma unroll
;   for (int r = 0; r < 16; ++r) ps += p0[r];
; #pragma unroll
;   for (int r = 0; r < 16; ++r) ps += p1[r];
;   { auto rr = __builtin_amdgcn_permlane32_swap(__float_as_uint(ps), __float_as_uint(ps), false, false);
;     ps = __uint_as_float(rr[0]) + __uint_as_float(rr[1]); }
;   l_reg = l_reg * alpha + ps;
;     ...
;   PK4(p0, 0, pa0); PK4(p0, 8, pa1); PK4(p1, 0, pa2); PK4(p1, 8, pa3);
;     ...
; }
; __device__ __forceinline__ void qkt(f32x16& p0, f32x16& p1, const bf16_t* Ks, const bf16x8* qr, int r32, int hi) {
;   p0 = f32x16{}; p1 = f32x16{};
; #pragma unroll
;   for (int d0 = 0; d0 < 8; ++d0) { int cb = (d0 * 16 + hi * 8) * 2;
;     bf16x8 b0 = *reinterpret_cast<const bf16x8*>((const char*)Ks + KSWZ(r32, cb));
;     bf16x8 b1 = *reinterpret_cast<const bf16x8*>((const char*)Ks + KSWZ(32 + r32, cb));
;     p0 = __builtin_amdgcn_mfma_f32_32x32x16_bf16(b0, qr[d0], p0, 0, 0, 0);
;     p1 = __builtin_amdgcn_mfma_f32_32x32x16_bf16(b1, qr[d0], p1, 0, 0, 0); }
; }
; template <bool META>
; __device__ __forceinline__ void attn_unit(const bf16_t* Q, bf16_t* Oo, const bf16_t* __restrict__ Kb, const bf16_t* __restrict__ Vb, int b, int kvh, int h, int qb, char* lds, const int tid, const float* qn, const float* RT) {
;     ...
;     SBAR(); qkt(pB0, pB1, (bf16_t*)((char*)K_lds + bc * SHM_K), qr, r32, hi);
;     finishSM(pA0, pA1, alA, l_reg, pa0, pa1, pa2, pa3); SBAR();
;     SLOAD(SO, j + 1);
;     SBAR();
;     pv_d0(o, vb0 + bp * (int)SHM_V, pa0, pa1, pa2, pa3); partialSM(pB0, pB1, m_reg, mnB, alB);
.LBB0_260:
	s_mov_b32 s6, s28
	v_sub_co_u32_e64 v66, s[0:1], s6, 1
	s_and_b64 s[0:1], s[0:1], exec
	v_readfirstlane_b32 s0, v66
	s_cselect_b32 s28, 2, s0
	s_lshl_b32 s9, s6, 14
	s_add_i32 s0, s9, 0
	v_add_u32_e32 v70, s0, v182
	ds_read_b128 v[66:69], v70 offset:49152
	ds_read_b128 v[70:73], v70 offset:57344
	v_add_u32_e32 v193, s0, v183
	ds_read_b128 v[210:213], v193 offset:49152
	ds_read_b128 v[214:217], v193 offset:57344
	v_add_u32_e32 v193, s0, v184
	s_waitcnt lgkmcnt(3)
	v_mfma_f32_32x32x16_bf16 v[82:97], v[66:69], v[98:101], 0
	v_exp_f32_e32 v144, v144
	v_exp_f32_e32 v145, v145
	v_exp_f32_e32 v142, v142
	v_exp_f32_e32 v143, v143
	v_exp_f32_e32 v140, v140
	v_exp_f32_e32 v141, v141
	v_exp_f32_e32 v138, v138
	s_waitcnt lgkmcnt(2)
	v_mfma_f32_32x32x16_bf16 v[66:81], v[70:73], v[98:101], 0
	v_exp_f32_e32 v139, v139
	v_exp_f32_e32 v136, v136
	v_exp_f32_e32 v137, v137
	v_exp_f32_e32 v134, v134
	v_exp_f32_e32 v135, v135
	v_exp_f32_e32 v132, v132
	v_exp_f32_e32 v133, v133
	s_waitcnt lgkmcnt(1)
	v_mfma_f32_32x32x16_bf16 v[82:97], v[210:213], v[102:105], v[82:97]
	v_exp_f32_e32 v130, v130
	v_exp_f32_e32 v131, v131
	s_waitcnt lgkmcnt(0)
	v_mfma_f32_32x32x16_bf16 v[66:81], v[214:217], v[102:105], v[66:81]
	ds_read_b128 v[210:213], v193 offset:49152
	ds_read_b128 v[214:217], v193 offset:57344
	v_add_u32_e32 v193, s0, v185
	s_waitcnt lgkmcnt(1)
	v_mfma_f32_32x32x16_bf16 v[82:97], v[210:213], v[106:109], v[82:97]
	s_waitcnt lgkmcnt(0)
	v_mfma_f32_32x32x16_bf16 v[66:81], v[214:217], v[106:109], v[66:81]
	ds_read_b128 v[210:213], v193 offset:49152
	ds_read_b128 v[214:217], v193 offset:57344
	v_add_u32_e32 v193, s0, v186
	s_waitcnt lgkmcnt(1)
	v_mfma_f32_32x32x16_bf16 v[82:97], v[210:213], v[110:113], v[82:97]
	s_waitcnt lgkmcnt(0)
	v_mfma_f32_32x32x16_bf16 v[66:81], v[214:217], v[110:113], v[66:81]
	ds_read_b128 v[210:213], v193 offset:49152
	ds_read_b128 v[214:217], v193 offset:57344
	v_add_u32_e32 v193, s0, v187
	s_waitcnt lgkmcnt(1)
	v_mfma_f32_32x32x16_bf16 v[82:97], v[210:213], v[114:117], v[82:97]
	s_waitcnt lgkmcnt(0)
	v_mfma_f32_32x32x16_bf16 v[66:81], v[214:217], v[114:117], v[66:81]
	ds_read_b128 v[210:213], v193 offset:49152
	ds_read_b128 v[214:217], v193 offset:57344
	v_add_u32_e32 v193, s0, v188
	s_waitcnt lgkmcnt(1)
	v_mfma_f32_32x32x16_bf16 v[82:97], v[210:213], v[118:121], v[82:97]
	s_waitcnt lgkmcnt(0)
	v_mfma_f32_32x32x16_bf16 v[66:81], v[214:217], v[118:121], v[66:81]
	ds_read_b128 v[210:213], v193 offset:49152
	ds_read_b128 v[214:217], v193 offset:57344
	v_add_u32_e32 v193, s0, v189
	s_waitcnt lgkmcnt(1)
	v_mfma_f32_32x32x16_bf16 v[82:97], v[210:213], v[122:125], v[82:97]
	s_waitcnt lgkmcnt(0)
	v_mfma_f32_32x32x16_bf16 v[66:81], v[214:217], v[122:125], v[66:81]
	ds_read_b128 v[210:213], v193 offset:49152
	ds_read_b128 v[214:217], v193 offset:57344
	v_add_f32_e32 v193, 0, v146
	v_add_f32_e32 v193, v147, v193
	v_add_f32_e32 v193, v148, v193
	v_add_f32_e32 v193, v159, v193
	v_add_f32_e32 v193, v160, v193
	v_add_f32_e32 v193, v209, v193
	v_add_f32_e32 v193, v149, v193
	v_add_f32_e32 v193, v161, v193
	v_add_f32_e32 v193, v151, v193
	v_add_f32_e32 v193, v153, v193
	v_add_f32_e32 v193, v154, v193
	v_add_f32_e32 v193, v157, v193
	v_add_f32_e32 v193, v152, v193
	v_add_f32_e32 v193, v155, v193
	v_add_f32_e32 v193, v156, v193
	v_add_f32_e32 v193, v158, v193
	v_add_f32_e32 v193, v144, v193
	v_add_f32_e32 v193, v145, v193
	v_add_f32_e32 v193, v142, v193
	v_add_f32_e32 v193, v143, v193
	v_add_f32_e32 v193, v140, v193
	v_add_f32_e32 v193, v141, v193
	v_add_f32_e32 v193, v138, v193
	v_add_f32_e32 v193, v139, v193
	v_add_f32_e32 v193, v136, v193
	v_add_f32_e32 v193, v137, v193
	s_waitcnt lgkmcnt(1)
	v_mfma_f32_32x32x16_bf16 v[82:97], v[210:213], v[126:129], v[82:97]
	v_add_f32_e32 v193, v134, v193
	v_add_f32_e32 v193, v135, v193
	v_add_f32_e32 v193, v132, v193
	v_add_f32_e32 v193, v133, v193
	v_add_f32_e32 v193, v130, v193
	v_add_f32_e32 v193, v131, v193
	v_mov_b32_e32 v195, v193
	s_waitcnt lgkmcnt(0)
	v_mfma_f32_32x32x16_bf16 v[66:81], v[214:217], v[126:129], v[66:81]
	v_cvt_pk_bf16_f32 v146, v146, v147
	v_cvt_pk_bf16_f32 v147, v148, v159
	v_cvt_pk_bf16_f32 v148, v160, v209
	v_permlane32_swap_b32_e32 v193, v195
	v_cvt_pk_bf16_f32 v149, v149, v161
	v_permlane32_swap_b32_e32 v146, v148
	v_cvt_pk_bf16_f32 v210, v151, v153
	v_cvt_pk_bf16_f32 v211, v154, v157
	v_cvt_pk_bf16_f32 v212, v152, v155
	v_cvt_pk_bf16_f32 v213, v156, v158
	v_cvt_pk_bf16_f32 v152, v144, v145
	v_cvt_pk_bf16_f32 v153, v142, v143
	v_cvt_pk_bf16_f32 v154, v140, v141
	v_cvt_pk_bf16_f32 v155, v138, v139
	v_cvt_pk_bf16_f32 v156, v136, v137
	v_cvt_pk_bf16_f32 v157, v134, v135
	v_cvt_pk_bf16_f32 v158, v132, v133
	v_cvt_pk_bf16_f32 v159, v130, v131
	v_permlane32_swap_b32_e32 v147, v149
	v_permlane32_swap_b32_e32 v210, v212
	v_permlane32_swap_b32_e32 v211, v213
	v_permlane32_swap_b32_e32 v152, v154
	v_permlane32_swap_b32_e32 v153, v155
	v_permlane32_swap_b32_e32 v156, v158
	v_permlane32_swap_b32_e32 v157, v159
	s_cmpk_lg_i32 s4, 0xfd
	s_cselect_b64 s[0:1], -1, 0
	s_cmpk_eq_i32 s4, 0xfd
	s_cselect_b64 s[40:41], -1, 0
	s_and_b64 s[10:11], s[40:41], exec
	s_cselect_b32 s11, s44, s91
	s_cselect_b32 s10, s31, s90
	s_lshl_b64 s[10:11], s[10:11], 9
	v_lshl_add_u64 v[130:131], v[168:169], 0, s[10:11]
	v_add_co_u32_e32 v134, vcc, s37, v130
	v_lshl_add_u64 v[138:139], v[170:171], 0, s[10:11]
	s_nop 0
	v_addc_co_u32_e32 v135, vcc, 0, v131, vcc
	v_add_co_u32_e32 v142, vcc, s37, v138
	global_load_dwordx4 v[130:133], v[130:131], off
	s_nop 0
	global_load_dwordx4 v[134:137], v[134:135], off
	v_addc_co_u32_e32 v143, vcc, 0, v139, vcc
	global_load_dwordx4 v[138:141], v[138:139], off
	s_nop 0
	global_load_dwordx4 v[142:145], v[142:143], off
	s_lshl_b32 s8, s28, 14
	v_add_u32_e32 v151, s8, v178
	ds_read_b64_tr_b16 v[214:215], v151 offset:0
	ds_read_b64_tr_b16 v[216:217], v151 offset:0x800
	ds_read_b64_tr_b16 v[218:219], v151 offset:0x1000
	ds_read_b64_tr_b16 v[220:221], v151 offset:0x1800
	ds_read_b64_tr_b16 v[222:223], v151 offset:0x2000
	ds_read_b64_tr_b16 v[224:225], v151 offset:0x2800
	ds_read_b64_tr_b16 v[226:227], v151 offset:0x3000
	ds_read_b64_tr_b16 v[228:229], v151 offset:0x3800
	s_waitcnt lgkmcnt(6)
; #define SBAR() __builtin_amdgcn_sched_barrier(0)
; __device__ __forceinline__ void partialSM(f32x16& p0, f32x16& p1, float& m_reg, float& mn, float& alpha) {
;   constexpr float C = ASCALE * 1.4426950408889634f;
;   float pmax = p0[0];
; #pragma unroll
;   for (int r = 1; r < 16; ++r) pmax = fmaxf(pmax, p0[r]);
; #pragma unroll
;   for (int r = 0; r < 16; ++r) pmax = fmaxf(pmax, p1[r]);
;   { auto rr = __builtin_amdgcn_permlane32_swap(__float_as_uint(pmax), __float_as_uint(pmax), false, false);
;     pmax = fmaxf(__uint_as_float(rr[0]), __uint_as_float(rr[1])); }
;   if (__builtin_expect(__all(pmax - m_reg <= ATHR / ASCALE), 1)) { mn = m_reg; alpha = 1.f; }
;   else { mn = fmaxf(m_reg, pmax); alpha = __builtin_amdgcn_exp2f((m_reg - mn) * C); m_reg = mn; }
; template <int D0> __device__ __forceinline__ void pv_one(f32x16& od, int vb, bf16x8 pa0, bf16x8 pa1, bf16x8 pa2, bf16x8 pa3) {
;   const s16x4 l0 = tr_read<v_rd_off(D0, 0, 0)>(vb), h0 = tr_read<v_rd_off(D0, 0, 1)>(vb), l1 = tr_read<v_rd_off(D0, 1, 0)>(vb), h1 = tr_read<v_rd_off(D0, 1, 1)>(vb);
;   const s16x4 l2 = tr_read<v_rd_off(D0, 2, 0)>(vb), h2 = tr_read<v_rd_off(D0, 2, 1)>(vb), l3 = tr_read<v_rd_off(D0, 3, 0)>(vb), h3 = tr_read<v_rd_off(D0, 3, 1)>(vb);
;   asm volatile("s_waitcnt lgkmcnt(0)" ::: "memory"); SBAR();
;     ...
;   od = __builtin_amdgcn_mfma_f32_32x32x16_bf16(pa0, PK(l0, h0), od, 0, 0, 0);
;   od = __builtin_amdgcn_mfma_f32_32x32x16_bf16(pa1, PK(l1, h1), od, 0, 0, 0);
;   od = __builtin_amdgcn_mfma_f32_32x32x16_bf16(pa2, PK(l2, h2), od, 0, 0, 0);
;   od = __builtin_amdgcn_mfma_f32_32x32x16_bf16(pa3, PK(l3, h3), od, 0, 0, 0);
;     ...
; }
; __device__ __forceinline__ void pv_d0(f32x16* o, int vb, bf16x8 pa0, bf16x8 pa1, bf16x8 pa2, bf16x8 pa3) {
;   pv_one<0>(o[0], vb, pa0, pa1, pa2, pa3); pv_one<1>(o[1], vb, pa0, pa1, pa2, pa3); pv_one<2>(o[2], vb, pa0, pa1, pa2, pa3); pv_one<3>(o[3], vb, pa0, pa1, pa2, pa3);
; }
	s_nop 0
	v_mfma_f32_32x32x16_bf16 v[2:17], v[146:149], v[214:217], v[2:17]
	ds_read_b64_tr_b16 v[214:215], v151 offset:0x200
	ds_read_b64_tr_b16 v[216:217], v151 offset:0xa00
	s_waitcnt lgkmcnt(6)
	v_mfma_f32_32x32x16_bf16 v[2:17], v[210:213], v[218:221], v[2:17]
	ds_read_b64_tr_b16 v[218:219], v151 offset:0x1200
	ds_read_b64_tr_b16 v[220:221], v151 offset:0x1a00
	s_waitcnt lgkmcnt(6)
	v_mfma_f32_32x32x16_bf16 v[2:17], v[152:155], v[222:225], v[2:17]
	ds_read_b64_tr_b16 v[222:223], v151 offset:0x2200
	ds_read_b64_tr_b16 v[224:225], v151 offset:0x2a00
	s_waitcnt lgkmcnt(6)
	v_mfma_f32_32x32x16_bf16 v[2:17], v[156:159], v[226:229], v[2:17]
	ds_read_b64_tr_b16 v[226:227], v151 offset:0x3200
	ds_read_b64_tr_b16 v[228:229], v151 offset:0x3a00
	s_waitcnt lgkmcnt(6)
	v_mfma_f32_32x32x16_bf16 v[50:65], v[146:149], v[214:217], v[50:65]
	ds_read_b64_tr_b16 v[214:215], v151 offset:0x400
	ds_read_b64_tr_b16 v[216:217], v151 offset:0xc00
	s_waitcnt lgkmcnt(6)
	v_mfma_f32_32x32x16_bf16 v[50:65], v[210:213], v[218:221], v[50:65]
	ds_read_b64_tr_b16 v[218:219], v151 offset:0x1400
	ds_read_b64_tr_b16 v[220:221], v151 offset:0x1c00
	s_waitcnt lgkmcnt(6)
	v_mfma_f32_32x32x16_bf16 v[50:65], v[152:155], v[222:225], v[50:65]
	ds_read_b64_tr_b16 v[222:223], v151 offset:0x2400
	ds_read_b64_tr_b16 v[224:225], v151 offset:0x2c00
	s_waitcnt lgkmcnt(6)
	v_mfma_f32_32x32x16_bf16 v[50:65], v[156:159], v[226:229], v[50:65]
	ds_read_b64_tr_b16 v[226:227], v151 offset:0x3400
	ds_read_b64_tr_b16 v[228:229], v151 offset:0x3c00
	s_waitcnt lgkmcnt(6)
	v_mfma_f32_32x32x16_bf16 v[34:49], v[146:149], v[214:217], v[34:49]
	ds_read_b64_tr_b16 v[214:215], v151 offset:0x600
	ds_read_b64_tr_b16 v[216:217], v151 offset:0xe00
	s_waitcnt lgkmcnt(6)
	v_mfma_f32_32x32x16_bf16 v[34:49], v[210:213], v[218:221], v[34:49]
	ds_read_b64_tr_b16 v[218:219], v151 offset:0x1600
	ds_read_b64_tr_b16 v[220:221], v151 offset:0x1e00
	s_waitcnt lgkmcnt(6)
	v_mfma_f32_32x32x16_bf16 v[34:49], v[152:155], v[222:225], v[34:49]
	ds_read_b64_tr_b16 v[222:223], v151 offset:0x2600
	ds_read_b64_tr_b16 v[224:225], v151 offset:0x2e00
	s_waitcnt lgkmcnt(6)
	v_mfma_f32_32x32x16_bf16 v[34:49], v[156:159], v[226:229], v[34:49]
	ds_read_b64_tr_b16 v[226:227], v151 offset:0x3600
	ds_read_b64_tr_b16 v[228:229], v151 offset:0x3e00
	s_waitcnt lgkmcnt(6)
	v_mfma_f32_32x32x16_bf16 v[18:33], v[146:149], v[214:217], v[18:33]
	v_max_f32_e32 v146, v83, v83
	v_max_f32_e32 v147, v82, v82
	v_max_f32_e32 v146, v147, v146
	v_max3_f32 v146, v146, v84, v85
	v_max3_f32 v146, v146, v86, v87
	v_max3_f32 v146, v146, v88, v89
	v_max3_f32 v146, v146, v90, v91
	v_max3_f32 v146, v146, v92, v93
	v_max3_f32 v146, v146, v94, v95
	v_max3_f32 v146, v146, v96, v97
	v_max3_f32 v146, v146, v66, v67
	s_waitcnt lgkmcnt(4)
	v_mfma_f32_32x32x16_bf16 v[18:33], v[210:213], v[218:221], v[18:33]
	v_max3_f32 v146, v146, v68, v69
	v_max3_f32 v146, v146, v70, v71
	v_max3_f32 v146, v146, v72, v73
	v_max3_f32 v146, v146, v74, v75
	v_max3_f32 v146, v146, v76, v77
	v_max3_f32 v146, v146, v78, v79
	v_max3_f32 v146, v146, v80, v81
	v_mov_b32_e32 v147, v146
	s_waitcnt lgkmcnt(2)
	v_mfma_f32_32x32x16_bf16 v[18:33], v[152:155], v[222:225], v[18:33]
	s_nop 0
	v_permlane32_swap_b32_e32 v146, v147
	v_max_f32_e32 v147, v147, v147
	v_max_f32_e32 v146, v146, v146
	v_max_f32_e32 v146, v146, v147
	v_sub_f32_e32 v147, v146, v150
	v_cmp_ge_f32_e32 vcc, s25, v147
	v_max_f32_e32 v147, v150, v150
	v_max_f32_e32 v146, v147, v146
	v_sub_f32_e32 v147, v150, v146
	s_cmp_eq_u64 vcc, exec
	v_mul_f32_e32 v147, 0x3e0293ee, v147
	s_waitcnt lgkmcnt(0)
	v_mfma_f32_32x32x16_bf16 v[18:33], v[156:159], v[226:229], v[18:33]
	s_cselect_b64 s[42:43], -1, 0
	v_exp_f32_e32 v147, v147
	s_add_i32 s7, s9, 0x4000
	s_cmp_lg_u32 s6, 2
	s_cselect_b32 s6, s7, 0
	s_add_i32 s10, s6, 0
	v_cndmask_b32_e64 v196, v147, 1.0, s[42:43]
	v_add_u32_e32 v147, s10, v176
	s_waitcnt vmcnt(0)
	s_waitcnt vmcnt(3)
	ds_write_b128 v147, v[130:133]
	v_add_u32_e32 v147, s10, v177
	s_waitcnt vmcnt(2)
	ds_write_b128 v147, v[134:137]
	v_add_u32_e32 v147, s10, v179
	s_waitcnt vmcnt(1)
	ds_write_b128 v147, v[138:141] offset:49152
	v_add_u32_e32 v147, s10, v180
	v_cmp_gt_f32_e32 vcc, 1.0, v196
	s_waitcnt vmcnt(0)
	ds_write_b128 v147, v[142:145] offset:49152
	s_cbranch_vccz .LBB0_264
	s_and_saveexec_b64 s[6:7], s[38:39]
	ds_write_b32 v190, v196 offset:128
	s_or_b64 exec, exec, s[6:7]
	s_waitcnt lgkmcnt(0)
	v_add_u32_e32 v147, v173, v181
	ds_read_b128 v[152:155], v147 offset:224
	ds_read_b128 v[156:159], v147 offset:192
	ds_read_b128 v[210:213], v147 offset:160
	ds_read_b128 v[214:217], v147 offset:128
	s_waitcnt lgkmcnt(3)
	v_pk_mul_f32 v[14:15], v[14:15], v[152:153]
	s_waitcnt lgkmcnt(2)
	v_pk_mul_f32 v[10:11], v[10:11], v[156:157]
	s_waitcnt lgkmcnt(1)
	v_pk_mul_f32 v[6:7], v[6:7], v[210:211]
	v_pk_mul_f32 v[16:17], v[16:17], v[154:155]
	v_pk_mul_f32 v[12:13], v[12:13], v[158:159]
	v_pk_mul_f32 v[8:9], v[8:9], v[212:213]
	s_waitcnt lgkmcnt(0)
	v_pk_mul_f32 v[4:5], v[4:5], v[216:217]
	v_pk_mul_f32 v[2:3], v[2:3], v[214:215]
	v_pk_mul_f32 v[62:63], v[62:63], v[152:153]
	v_pk_mul_f32 v[58:59], v[58:59], v[156:157]
	v_pk_mul_f32 v[54:55], v[54:55], v[210:211]
	v_pk_mul_f32 v[64:65], v[64:65], v[154:155]
	v_pk_mul_f32 v[60:61], v[60:61], v[158:159]
	v_pk_mul_f32 v[56:57], v[56:57], v[212:213]
	v_pk_mul_f32 v[52:53], v[52:53], v[216:217]
	v_pk_mul_f32 v[50:51], v[50:51], v[214:215]
	v_pk_mul_f32 v[46:47], v[46:47], v[152:153]
	v_pk_mul_f32 v[42:43], v[42:43], v[156:157]
	v_pk_mul_f32 v[38:39], v[38:39], v[210:211]
	v_pk_mul_f32 v[48:49], v[48:49], v[154:155]
	v_pk_mul_f32 v[44:45], v[44:45], v[158:159]
	v_pk_mul_f32 v[40:41], v[40:41], v[212:213]
	v_pk_mul_f32 v[36:37], v[36:37], v[216:217]
	v_pk_mul_f32 v[34:35], v[34:35], v[214:215]
	v_pk_mul_f32 v[30:31], v[30:31], v[152:153]
	v_pk_mul_f32 v[26:27], v[26:27], v[156:157]
	v_pk_mul_f32 v[22:23], v[22:23], v[210:211]
	v_pk_mul_f32 v[32:33], v[32:33], v[154:155]
	v_pk_mul_f32 v[28:29], v[28:29], v[158:159]
	v_pk_mul_f32 v[24:25], v[24:25], v[212:213]
	v_pk_mul_f32 v[20:21], v[20:21], v[216:217]
	v_pk_mul_f32 v[18:19], v[18:19], v[214:215]

; #define SBAR() __builtin_amdgcn_sched_barrier(0)
; __device__ __forceinline__ void partialSM(f32x16& p0, f32x16& p1, float& m_reg, float& mn, float& alpha) {
;   constexpr float C = ASCALE * 1.4426950408889634f;
;   float pmax = p0[0];
; #pragma unroll
;   for (int r = 1; r < 16; ++r) pmax = fmaxf(pmax, p0[r]);
; #pragma unroll
;   for (int r = 0; r < 16; ++r) pmax = fmaxf(pmax, p1[r]);
;   { auto rr = __builtin_amdgcn_permlane32_swap(__float_as_uint(pmax), __float_as_uint(pmax), false, false);
;     pmax = fmaxf(__uint_as_float(rr[0]), __uint_as_float(rr[1])); }
;   if (__builtin_expect(__all(pmax - m_reg <= ATHR / ASCALE), 1)) { mn = m_reg; alpha = 1.f; }
;   else { mn = fmaxf(m_reg, pmax); alpha = __builtin_amdgcn_exp2f((m_reg - mn) * C); m_reg = mn; }
; template <int D0> __device__ __forceinline__ void pv_one(f32x16& od, int vb, bf16x8 pa0, bf16x8 pa1, bf16x8 pa2, bf16x8 pa3) {
;   const s16x4 l0 = tr_read<v_rd_off(D0, 0, 0)>(vb), h0 = tr_read<v_rd_off(D0, 0, 1)>(vb), l1 = tr_read<v_rd_off(D0, 1, 0)>(vb), h1 = tr_read<v_rd_off(D0, 1, 1)>(vb);
;   const s16x4 l2 = tr_read<v_rd_off(D0, 2, 0)>(vb), h2 = tr_read<v_rd_off(D0, 2, 1)>(vb), l3 = tr_read<v_rd_off(D0, 3, 0)>(vb), h3 = tr_read<v_rd_off(D0, 3, 1)>(vb);
;   asm volatile("s_waitcnt lgkmcnt(0)" ::: "memory"); SBAR();
;     ...
;   od = __builtin_amdgcn_mfma_f32_32x32x16_bf16(pa0, PK(l0, h0), od, 0, 0, 0);
;   od = __builtin_amdgcn_mfma_f32_32x32x16_bf16(pa1, PK(l1, h1), od, 0, 0, 0);
;   od = __builtin_amdgcn_mfma_f32_32x32x16_bf16(pa2, PK(l2, h2), od, 0, 0, 0);
;   od = __builtin_amdgcn_mfma_f32_32x32x16_bf16(pa3, PK(l3, h3), od, 0, 0, 0);
;     ...
; }
; __device__ __forceinline__ void pv_d0(f32x16* o, int vb, bf16x8 pa0, bf16x8 pa1, bf16x8 pa2, bf16x8 pa3) {
;   pv_one<0>(o[0], vb, pa0, pa1, pa2, pa3); pv_one<1>(o[1], vb, pa0, pa1, pa2, pa3); pv_one<2>(o[2], vb, pa0, pa1, pa2, pa3); pv_one<3>(o[3], vb, pa0, pa1, pa2, pa3);
; }
; __device__ __forceinline__ void mask_last(f32x16& p0, f32x16& p1) {
; #pragma unroll
;   for (int r = 8; r < 16; ++r) p0[r] = -1e30f;
; #pragma unroll
;   for (int r = 0; r < 16; ++r) p1[r] = -1e30f;
; }
.LBB0_266:
	v_cndmask_b32_e64 v212, v81, v246, s[40:41]
	v_cndmask_b32_e64 v213, v80, v246, s[40:41]
	v_cndmask_b32_e64 v214, v79, v246, s[40:41]
	v_cndmask_b32_e64 v215, v78, v246, s[40:41]
	v_cndmask_b32_e64 v216, v77, v246, s[40:41]
	v_cndmask_b32_e64 v217, v76, v246, s[40:41]
	v_cndmask_b32_e64 v218, v75, v246, s[40:41]
	v_cndmask_b32_e64 v219, v74, v246, s[40:41]
	v_cndmask_b32_e64 v75, v97, v246, s[40:41]
	v_cndmask_b32_e64 v74, v96, v246, s[40:41]
	v_cndmask_b32_e64 v77, v95, v246, s[40:41]
	v_cndmask_b32_e64 v76, v94, v246, s[40:41]
	v_cndmask_b32_e64 v79, v93, v246, s[40:41]
	v_cndmask_b32_e64 v78, v92, v246, s[40:41]
	v_cndmask_b32_e64 v81, v91, v246, s[40:41]
	v_cndmask_b32_e64 v80, v90, v246, s[40:41]
	v_cndmask_b32_e64 v89, v89, v246, s[40:41]
	v_cndmask_b32_e64 v88, v88, v246, s[40:41]
	v_cndmask_b32_e64 v87, v87, v246, s[40:41]
	v_cndmask_b32_e64 v86, v86, v246, s[40:41]
	v_cndmask_b32_e64 v85, v85, v246, s[40:41]
	v_cndmask_b32_e64 v84, v84, v246, s[40:41]
	v_cndmask_b32_e64 v83, v83, v246, s[40:41]
	v_cndmask_b32_e64 v82, v82, v246, s[40:41]
	v_add_u32_e32 v198, s9, v178
	ds_read_b64_tr_b16 v[90:91], v198 offset:0
	ds_read_b64_tr_b16 v[92:93], v198 offset:0x800
	ds_read_b64_tr_b16 v[94:95], v198 offset:0x1000
	ds_read_b64_tr_b16 v[96:97], v198 offset:0x1800
	ds_read_b64_tr_b16 v[220:221], v198 offset:0x2000
	ds_read_b64_tr_b16 v[222:223], v198 offset:0x2800
	ds_read_b64_tr_b16 v[224:225], v198 offset:0x3000
	ds_read_b64_tr_b16 v[226:227], v198 offset:0x3800
	s_waitcnt lgkmcnt(6)
	s_nop 0
	v_mfma_f32_32x32x16_bf16 v[2:17], v[146:149], v[90:93], v[2:17]
	ds_read_b64_tr_b16 v[90:91], v198 offset:0x200
	ds_read_b64_tr_b16 v[92:93], v198 offset:0xa00
	s_waitcnt lgkmcnt(6)
	v_mfma_f32_32x32x16_bf16 v[2:17], v[150:153], v[94:97], v[2:17]
	ds_read_b64_tr_b16 v[94:95], v198 offset:0x1200
	ds_read_b64_tr_b16 v[96:97], v198 offset:0x1a00
	s_waitcnt lgkmcnt(6)
	v_mfma_f32_32x32x16_bf16 v[2:17], v[154:157], v[220:223], v[2:17]
	ds_read_b64_tr_b16 v[220:221], v198 offset:0x2200
	ds_read_b64_tr_b16 v[222:223], v198 offset:0x2a00
	s_waitcnt lgkmcnt(6)
	v_mfma_f32_32x32x16_bf16 v[2:17], v[158:161], v[224:227], v[2:17]
	ds_read_b64_tr_b16 v[224:225], v198 offset:0x3200
	ds_read_b64_tr_b16 v[226:227], v198 offset:0x3a00
	s_waitcnt lgkmcnt(6)
	v_mfma_f32_32x32x16_bf16 v[50:65], v[146:149], v[90:93], v[50:65]
	ds_read_b64_tr_b16 v[90:91], v198 offset:0x400
	ds_read_b64_tr_b16 v[92:93], v198 offset:0xc00
	s_waitcnt lgkmcnt(6)
	v_mfma_f32_32x32x16_bf16 v[50:65], v[150:153], v[94:97], v[50:65]
	ds_read_b64_tr_b16 v[94:95], v198 offset:0x1400
	ds_read_b64_tr_b16 v[96:97], v198 offset:0x1c00
	s_waitcnt lgkmcnt(6)
	v_mfma_f32_32x32x16_bf16 v[50:65], v[154:157], v[220:223], v[50:65]
	ds_read_b64_tr_b16 v[220:221], v198 offset:0x2400
	ds_read_b64_tr_b16 v[222:223], v198 offset:0x2c00
	s_waitcnt lgkmcnt(6)
	v_mfma_f32_32x32x16_bf16 v[50:65], v[158:161], v[224:227], v[50:65]
	ds_read_b64_tr_b16 v[224:225], v198 offset:0x3400
	ds_read_b64_tr_b16 v[226:227], v198 offset:0x3c00
	s_waitcnt lgkmcnt(6)
	v_mfma_f32_32x32x16_bf16 v[34:49], v[146:149], v[90:93], v[34:49]
	ds_read_b64_tr_b16 v[90:91], v198 offset:0x600
	ds_read_b64_tr_b16 v[92:93], v198 offset:0xe00
	s_waitcnt lgkmcnt(6)
	v_mfma_f32_32x32x16_bf16 v[34:49], v[150:153], v[94:97], v[34:49]
	ds_read_b64_tr_b16 v[94:95], v198 offset:0x1600
	ds_read_b64_tr_b16 v[96:97], v198 offset:0x1e00
	s_waitcnt lgkmcnt(6)
	v_mfma_f32_32x32x16_bf16 v[34:49], v[154:157], v[220:223], v[34:49]
	ds_read_b64_tr_b16 v[220:221], v198 offset:0x2600
	ds_read_b64_tr_b16 v[222:223], v198 offset:0x2e00
	s_waitcnt lgkmcnt(6)
	v_mfma_f32_32x32x16_bf16 v[34:49], v[158:161], v[224:227], v[34:49]
	ds_read_b64_tr_b16 v[224:225], v198 offset:0x3600
	ds_read_b64_tr_b16 v[226:227], v198 offset:0x3e00
	s_waitcnt lgkmcnt(6)
	v_mfma_f32_32x32x16_bf16 v[18:33], v[146:149], v[90:93], v[18:33]
	v_max_f32_e32 v90, v67, v67
	v_max_f32_e32 v91, v66, v66
	v_max_f32_e32 v90, v91, v90
	v_max3_f32 v90, v90, v68, v69
	v_max3_f32 v90, v90, v70, v71
	v_max3_f32 v90, v90, v72, v73
	v_max3_f32 v90, v90, v219, v218
	v_max3_f32 v90, v90, v217, v216
	v_max3_f32 v90, v90, v215, v214
	s_waitcnt lgkmcnt(4)
	v_mfma_f32_32x32x16_bf16 v[18:33], v[150:153], v[94:97], v[18:33]
	v_max3_f32 v90, v90, v213, v212
	v_max3_f32 v90, v90, v82, v83
	v_max3_f32 v90, v90, v84, v85
	v_max3_f32 v90, v90, v86, v87
	v_max3_f32 v90, v90, v88, v89
	v_max3_f32 v90, v90, v80, v81
	v_max3_f32 v90, v90, v78, v79
	v_max3_f32 v90, v90, v76, v77
	s_waitcnt lgkmcnt(2)
	v_mfma_f32_32x32x16_bf16 v[18:33], v[154:157], v[220:223], v[18:33]
	v_max3_f32 v90, v90, v74, v75
	v_mov_b32_e32 v91, v90
	s_nop 1
	v_permlane32_swap_b32_e32 v90, v91
	v_max_f32_e32 v91, v91, v91
	v_max_f32_e32 v90, v90, v90
	v_max_f32_e32 v90, v90, v91
	v_sub_f32_e32 v91, v90, v209
	v_cmp_ge_f32_e32 vcc, s25, v91
	v_max_f32_e32 v91, v209, v209
	v_max_f32_e32 v91, v91, v90
	s_waitcnt lgkmcnt(0)
	v_mfma_f32_32x32x16_bf16 v[18:33], v[158:161], v[224:227], v[18:33]
	v_sub_f32_e32 v90, v209, v91
	v_mul_f32_e32 v90, 0x3e0293ee, v90
	s_cmp_eq_u64 vcc, exec
	v_exp_f32_e32 v90, v90
	s_cselect_b64 s[40:41], -1, 0
	s_add_i32 s0, s8, 0
	v_add_u32_e32 v92, s0, v176
	s_waitcnt vmcnt(0)
	s_waitcnt vmcnt(3)
	ds_write_b128 v92, v[130:133]
	v_add_u32_e32 v92, s0, v177
	v_cndmask_b32_e64 v90, v90, 1.0, s[40:41]
	s_waitcnt vmcnt(2)
	ds_write_b128 v92, v[134:137]
	v_add_u32_e32 v92, s0, v179
	s_waitcnt vmcnt(1)
	ds_write_b128 v92, v[138:141] offset:49152
	v_add_u32_e32 v92, s0, v180
	v_cmp_gt_f32_e32 vcc, 1.0, v90
	s_waitcnt vmcnt(0)
	ds_write_b128 v92, v[142:145] offset:49152
	s_cbranch_vccz .LBB0_270
	s_and_saveexec_b64 s[0:1], s[38:39]
	ds_write_b32 v190, v90 offset:128
	s_or_b64 exec, exec, s[0:1]
	s_waitcnt lgkmcnt(0)
	v_add_u32_e32 v96, v173, v181
	ds_read_b128 v[92:95], v96 offset:224
	ds_read_b128 v[130:133], v96 offset:192
	ds_read_b128 v[134:137], v96 offset:160
	ds_read_b128 v[138:141], v96 offset:128
	s_waitcnt lgkmcnt(3)
	v_pk_mul_f32 v[14:15], v[14:15], v[92:93]
	s_waitcnt lgkmcnt(2)
	v_pk_mul_f32 v[10:11], v[10:11], v[130:131]
	s_waitcnt lgkmcnt(1)
	v_pk_mul_f32 v[6:7], v[6:7], v[134:135]
	v_pk_mul_f32 v[16:17], v[16:17], v[94:95]
	v_pk_mul_f32 v[12:13], v[12:13], v[132:133]
	v_pk_mul_f32 v[8:9], v[8:9], v[136:137]
	s_waitcnt lgkmcnt(0)
	v_pk_mul_f32 v[4:5], v[4:5], v[140:141]
	v_pk_mul_f32 v[2:3], v[2:3], v[138:139]
	v_pk_mul_f32 v[62:63], v[62:63], v[92:93]
	v_pk_mul_f32 v[58:59], v[58:59], v[130:131]
	v_pk_mul_f32 v[54:55], v[54:55], v[134:135]
	v_pk_mul_f32 v[64:65], v[64:65], v[94:95]
	v_pk_mul_f32 v[60:61], v[60:61], v[132:133]
	v_pk_mul_f32 v[56:57], v[56:57], v[136:137]
	v_pk_mul_f32 v[52:53], v[52:53], v[140:141]
	v_pk_mul_f32 v[50:51], v[50:51], v[138:139]
	v_pk_mul_f32 v[46:47], v[46:47], v[92:93]
	v_pk_mul_f32 v[42:43], v[42:43], v[130:131]
	v_pk_mul_f32 v[38:39], v[38:39], v[134:135]
	v_pk_mul_f32 v[48:49], v[48:49], v[94:95]
	v_pk_mul_f32 v[44:45], v[44:45], v[132:133]
	v_pk_mul_f32 v[40:41], v[40:41], v[136:137]
	v_pk_mul_f32 v[36:37], v[36:37], v[140:141]
	v_pk_mul_f32 v[34:35], v[34:35], v[138:139]
	v_pk_mul_f32 v[30:31], v[30:31], v[92:93]
	v_pk_mul_f32 v[26:27], v[26:27], v[130:131]
	v_pk_mul_f32 v[22:23], v[22:23], v[134:135]
	v_pk_mul_f32 v[32:33], v[32:33], v[94:95]
	v_pk_mul_f32 v[28:29], v[28:29], v[132:133]
	v_pk_mul_f32 v[24:25], v[24:25], v[136:137]
	v_pk_mul_f32 v[20:21], v[20:21], v[140:141]
	v_pk_mul_f32 v[18:19], v[18:19], v[138:139]
